# HG in-proj tile order: 5th-round tiles swapped to cheap V tiles (balance), mamba dt prefix scan via DPP
# speedup vs baseline: 1.0126x; 1.0114x over previous
; __device__ __forceinline__ void mamba_block(ArgsP a_, unsigned char* smem) { const ArgsP a = a_;
;     ...
;         if (tid < 64) { const int j = tid; const bool valid = j < len; const float dtr = dtpre + AIN(22)[hd];
;             const float dt = valid ? (dtr > 20.f ? dtr : log1pf(__expf(dtr))) : 0.f; float x = -dt * __expf(AIN(23)[hd]);
; #pragma unroll
;             for (int off = 1; off < 64; off <<= 1) { const float t = __shfl_up(x, off); if (lane >= off) x += t; }
;             const float glast = __shfl(x, 63); GI[j] = x; DTV[j] = dt; W2[j] = dt * __expf(glast - x); const float ed = __expf(glast); SDEC[2 * j] = ed; SDEC[2 * j + 1] = ed; }
.LBB0_347:
	s_or_b64 exec, exec, s[76:77]
	v_mul_f32_e32 v18, 0x3fb8aa3b, v129
	v_exp_f32_e32 v18, v18
	s_nop 0
	v_mul_f32_e64 v18, v18, -v16
	s_nop 1
	v_add_f32_dpp v18, v18, v18 row_shr:1 row_mask:0xf bank_mask:0xf
	s_nop 1
	v_add_f32_dpp v18, v18, v18 row_shr:2 row_mask:0xf bank_mask:0xf
	s_nop 1
	v_add_f32_dpp v18, v18, v18 row_shr:4 row_mask:0xf bank_mask:0xf
	s_nop 1
	v_add_f32_dpp v18, v18, v18 row_shr:8 row_mask:0xf bank_mask:0xf
	s_nop 1
	v_add_f32_dpp v18, v18, v18 row_bcast:15 row_mask:0xa bank_mask:0xf
	s_nop 1
	v_add_f32_dpp v18, v18, v18 row_bcast:31 row_mask:0xc bank_mask:0xf
	v_lshl_or_b32 v19, v188, 2, v252
	ds_bpermute_b32 v19, v19, v18
	ds_write_b32 v69, v18
	ds_write_b32 v76, v16
	s_waitcnt lgkmcnt(2)
	v_sub_f32_e32 v18, v19, v18
	v_mul_f32_e32 v18, 0x3fb8aa3b, v18
	v_exp_f32_e32 v18, v18
	s_nop 0
	v_mul_f32_e32 v16, v16, v18
	ds_write_b32 v77, v16
	v_mul_f32_e32 v16, 0x3fb8aa3b, v19
	v_exp_f32_e32 v18, v16
	s_nop 0
	v_mov_b32_e32 v19, v18
	ds_write_b64 v108, v[18:19]

;     __device__ bool next(int i, Unit& u) const {
;     ...
;         const long L = (long)i * G + c; if (L >= (long)nwg * nS) return false;
;         u.s = (int)(L / nwg); int wgid = (int)(L % nwg);
;         { const int q = nwg / NXCD, r = nwg % NXCD, xcd = wgid % NXCD, off = wgid / NXCD; wgid = (xcd < r ? xcd * (q + 1) : r * (q + 1) + (xcd - r) * q) + off; }
;         const int nig = WGM * nN, gid = wgid / nig, fm = gid * WGM, gsz = (nM - fm) < WGM ? (nM - fm) : WGM;
;         u.pm = __builtin_amdgcn_readfirstlane(fm + ((wgid % nig) % gsz)); u.pn = __builtin_amdgcn_readfirstlane((wgid % nig) / gsz); u.s = __builtin_amdgcn_readfirstlane(u.s); u.kb = 0; u.nt = 0; u.full = 0; return true;
.LBB0_673:
	v_readlane_b32 s4, v255, 3
	s_cmpk_lt_i32 s4, 0x450
	v_mov_b32_e32 v9, v186
	s_cselect_b64 s[24:25], -1, 0
	s_cmpk_gt_i32 s4, 0x44f
	s_mov_b64 s[22:23], 0
	v_readfirstlane_b32 s69, v9
	s_cbranch_scc1 .LBB0_675
	v_readlane_b32 s5, v255, 3
	s_nop 3
	s_cmp_lt_u32 s5, 0x400
	s_cbranch_scc1 .Ltb_lo_a
	s_sub_u32 s4, s5, 0x400
	s_and_b32 s18, s4, 7
	s_lshr_b32 s4, s4, 3
	s_mul_i32 s19, s18, 10
	s_add_u32 s22, s4, s19
	s_add_u32 s22, s22, 10
	s_and_b32 s22, s22, 31
	s_sub_u32 s22, s22, s19
	s_add_u32 s22, s22, 64
	s_and_b32 s22, s22, 0x7f
	s_lshl_b32 s22, s22, 3
	s_or_b32 s5, s22, s18
	s_branch .Ltb_done_a
.Ltb_lo_a:
	s_and_b32 s18, s5, 7
	s_lshr_b32 s4, s5, 3
	s_and_b32 s19, s4, 31
	s_sub_u32 s19, s19, 10
	s_cmp_lt_u32 s19, 10
	s_cbranch_scc0 .Ltb_done_a
	s_mul_i32 s22, s18, 10
	s_add_u32 s19, s19, s22
	s_add_u32 s19, s19, 10
	s_and_b32 s19, s19, 31
	s_sub_u32 s19, s19, s22
	s_add_u32 s19, s19, 64
	s_and_b32 s19, s19, 0x7f
	s_cmp_eq_u32 s19, s4
	s_cbranch_scc0 .Ltb_done_a
	s_and_b32 s4, s4, 31
	s_sub_u32 s4, s4, 10
	s_lshl_b32 s4, s4, 3
	s_or_b32 s4, s4, s18
	s_or_b32 s5, s4, 0x400
.Ltb_done_a:
	s_mul_hi_i32 s19, s5, 0x76b981db
	s_lshr_b32 s22, s19, 31
	s_lshr_b32 s4, s19, 9
	s_add_i32 s4, s4, s22
	s_mulk_i32 s4, 0x450
	s_sub_i32 s4, s5, s4
	s_sext_i32_i16 s5, s4
	s_bfe_u32 s5, s5, 0x3001c
	s_add_i32 s5, s4, s5
	s_sext_i32_i16 s18, s5
	s_and_b32 s5, s5, 0xfff8
	s_sub_i32 s4, s4, s5
	s_ashr_i32 s18, s18, 3
	s_sext_i32_i16 s5, s4
	s_cmp_lt_i32 s5, 0
	s_movk_i32 s5, 0x8b
	s_cselect_b32 s5, s5, 0x8a
	s_mul_i32 s4, s5, s4
	s_add_i32 s4, s4, s18
	s_sext_i32_i16 s5, s4
	s_bfe_u32 s5, s5, 0x70018
	s_add_i32 s5, s4, s5
	s_sext_i32_i16 s18, s5
	s_ashr_i32 s18, s18, 7
	s_lshl_b32 s18, s18, 3
	s_sub_i32 s23, 0x45, s18
	s_and_b32 s5, s5, 0xff80
	s_min_u32 s23, s23, 8
	s_sub_i32 s26, s4, s5
	s_sext_i32_i16 s4, s26
	v_cvt_f32_ubyte0_e32 v1, s23
	v_cvt_f32_i32_e32 v0, s4
	v_rcp_iflag_f32_e32 v2, v1
	s_ashr_i32 s4, s4, 30
	s_or_b32 s27, s4, 1
	v_mul_f32_e32 v2, v0, v2
	v_trunc_f32_e32 v2, v2
	v_fma_f32 v0, -v2, v1, v0
	v_cvt_i32_f32_e32 v2, v2
	v_cmp_ge_f32_e64 s[4:5], |v0|, v1
	s_and_b64 s[4:5], s[4:5], exec
	s_cselect_b32 s4, s27, 0
	v_readfirstlane_b32 s5, v2
	s_add_i32 s5, s5, s4
	s_sext_i32_i8 s4, s5
	s_mul_i32 s5, s5, s23
	s_sub_i32 s5, s26, s5
	s_sext_i32_i8 s5, s5
	s_add_i32 s18, s18, s5
	s_ashr_i32 s5, s19, 9
	s_add_i32 s22, s5, s22
	s_ashr_i32 s23, s22, 31
	s_lshl_b64 s[22:23], s[22:23], 11

;     __device__ bool next(int i, Unit& u) const {
;     ...
;         const long L = (long)i * G + c; if (L >= (long)nwg * nS) return false;
;         u.s = (int)(L / nwg); int wgid = (int)(L % nwg);
;         { const int q = nwg / NXCD, r = nwg % NXCD, xcd = wgid % NXCD, off = wgid / NXCD; wgid = (xcd < r ? xcd * (q + 1) : r * (q + 1) + (xcd - r) * q) + off; }
;         const int nig = WGM * nN, gid = wgid / nig, fm = gid * WGM, gsz = (nM - fm) < WGM ? (nM - fm) : WGM;
;         u.pm = __builtin_amdgcn_readfirstlane(fm + ((wgid % nig) % gsz)); u.pn = __builtin_amdgcn_readfirstlane((wgid % nig) / gsz); u.s = __builtin_amdgcn_readfirstlane(u.s); u.kb = 0; u.nt = 0; u.full = 0; return true;
; template <class Epi, bool FP8>
; __device__ __forceinline__ void gemm_phase(LAS unsigned char* lds, const Gemm g, const SplitOrder& S, const Epi& E) {
;     ...
;         const bool has_next = S.next(ui + 1, nxt);
.LBB0_680:
	s_add_i32 s80, s80, 1
	s_mul_i32 s5, s80, s11
	s_mul_hi_u32 s19, s80, s10
	s_add_i32 s19, s19, s5
	s_mul_i32 s5, s80, s10
	v_readlane_b32 s26, v255, 3
	s_add_u32 s26, s5, s26
	s_addc_u32 s27, s19, s77
	v_cmp_gt_i64_e64 s[40:41], s[26:27], v[158:159]
	v_cmp_lt_i64_e64 s[42:43], s[26:27], v[156:157]
	s_and_b64 vcc, exec, s[40:41]
	s_cbranch_vccnz .LBB0_682
	s_cmp_lt_u32 s26, 0x400
	s_cbranch_scc1 .Ltb_lo_b
	s_sub_u32 s44, s26, 0x400
	s_and_b32 s45, s44, 7
	s_lshr_b32 s44, s44, 3
	s_mul_i32 s46, s45, 10
	s_add_u32 s47, s44, s46
	s_add_u32 s47, s47, 10
	s_and_b32 s47, s47, 31
	s_sub_u32 s47, s47, s46
	s_add_u32 s47, s47, 64
	s_and_b32 s47, s47, 0x7f
	s_lshl_b32 s47, s47, 3
	s_or_b32 s26, s47, s45
	s_branch .Ltb_done_b
.Ltb_lo_b:
	s_and_b32 s45, s26, 7
	s_lshr_b32 s44, s26, 3
	s_and_b32 s46, s44, 31
	s_sub_u32 s46, s46, 10
	s_cmp_lt_u32 s46, 10
	s_cbranch_scc0 .Ltb_done_b
	s_mul_i32 s47, s45, 10
	s_add_u32 s46, s46, s47
	s_add_u32 s46, s46, 10
	s_and_b32 s46, s46, 31
	s_sub_u32 s46, s46, s47
	s_add_u32 s46, s46, 64
	s_and_b32 s46, s46, 0x7f
	s_cmp_eq_u32 s46, s44
	s_cbranch_scc0 .Ltb_done_b
	s_and_b32 s44, s44, 31
	s_sub_u32 s44, s44, 10
	s_lshl_b32 s44, s44, 3
	s_or_b32 s44, s44, s45
	s_or_b32 s26, s44, 0x400
.Ltb_done_b:
	s_mul_i32 s47, s27, 0xe6076b99
	s_mul_hi_u32 s59, s26, 0xe6076b99
	s_mul_hi_u32 s46, s27, 0xe6076b99
	s_add_u32 s34, s47, s59
	s_mul_i32 s19, s26, 0x76b981da
	s_addc_u32 s35, s46, 0
	s_mul_hi_u32 s5, s26, 0x76b981da
	s_add_u32 s34, s19, s34
	s_addc_u32 s34, s5, 0
	s_add_u32 s34, s35, s34
	s_addc_u32 s35, 0, 0
	s_mul_i32 s62, s27, 0x76b981da
	s_mul_hi_u32 s61, s27, 0x76b981da
	s_add_u32 s34, s62, s34
	s_addc_u32 s35, s61, s35
	s_ashr_i32 s27, s27, 31
	s_mul_i32 s44, s27, 0x76b981da
	s_mul_hi_u32 s45, s27, 0xe6076b99
	s_add_i32 s44, s45, s44
	s_mul_i32 s63, s27, 0xe6076b99
	s_add_i32 s64, s44, s63
	s_add_u32 s34, s34, s63
	s_addc_u32 s35, s35, s64
	s_ashr_i64 s[44:45], s[34:35], 9
	s_lshr_b32 s27, s35, 31
	s_add_u32 s27, s44, s27
	s_mulk_i32 s27, 0x450
	s_sub_i32 s26, s26, s27
	s_sext_i32_i16 s27, s26
	s_bfe_u32 s27, s27, 0x3001c
	s_add_i32 s27, s26, s27
	s_sext_i32_i16 s34, s27
	s_and_b32 s27, s27, 0xfff8
	s_sub_i32 s26, s26, s27
	s_ashr_i32 s34, s34, 3
	s_sext_i32_i16 s27, s26
	s_cmp_lt_i32 s27, 0
	s_movk_i32 s27, 0x8b
	s_cselect_b32 s27, s27, 0x8a
	s_mul_i32 s26, s26, s27
	s_add_i32 s26, s26, s34
	s_sext_i32_i16 s27, s26
	s_bfe_u32 s27, s27, 0x70018
	s_add_i32 s27, s26, s27
	s_sext_i32_i16 s34, s27
	s_ashr_i32 s34, s34, 7
	s_lshl_b32 s34, s34, 3
	s_sub_i32 s35, 0x45, s34
	s_and_b32 s27, s27, 0xff80
	s_min_u32 s35, s35, 8
	s_sub_i32 s44, s26, s27
	s_sext_i32_i16 s26, s44
	v_cvt_f32_ubyte0_e32 v1, s35
	v_cvt_f32_i32_e32 v0, s26
	v_rcp_iflag_f32_e32 v2, v1
	s_ashr_i32 s26, s26, 30
	s_or_b32 s45, s26, 1
	v_mul_f32_e32 v2, v0, v2
	v_trunc_f32_e32 v2, v2
	v_fma_f32 v0, -v2, v1, v0
	v_cvt_i32_f32_e32 v2, v2
	v_cmp_ge_f32_e64 s[26:27], |v0|, v1
	s_and_b64 s[26:27], s[26:27], exec
	s_cselect_b32 s26, s45, 0
	v_readfirstlane_b32 s27, v2
	s_add_i32 s26, s27, s26
	s_sext_i32_i8 s58, s26
	s_mul_i32 s26, s26, s35
	s_sub_i32 s26, s44, s26
	s_sext_i32_i8 s26, s26
	s_add_i32 s60, s34, s26
	s_add_u32 s26, s47, s59
	s_addc_u32 s27, s46, 0
	s_add_u32 s19, s19, s26
	s_addc_u32 s5, s5, 0
	s_add_u32 s5, s27, s5
	s_addc_u32 s19, 0, 0
	s_add_u32 s5, s62, s5
	s_addc_u32 s19, s61, s19
	s_add_u32 s26, s5, s63
	s_addc_u32 s27, s19, s64
	s_lshr_b32 s5, s27, 31
	s_lshr_b64 s[26:27], s[26:27], 9
	s_add_i32 s62, s26, s5
